# FFN epilogue: n=0 conv weights issued ahead of the raw-row stores (counted vmcnt), SiLU fully packed; accumulator zeroing of all four GEMM phases as 64 v_mov_b64 instead of 128 v_mov_b32
# speedup vs baseline: 1.0308x; 1.0025x over previous
; template <class Epi, class Sched, bool ALIGN_EPI = false, bool SP2 = false>
; __device__ __forceinline__ void gemm_phase(PG8_LAS unsigned char* lds, const Gemm g, const Sched& S, const Epi& E) {
;     ...
;         const bool has_next = S.next(ui + 1, nxt);
;         const char* nA = has_next ? (const char*)g.A + (size_t)nxt.pm * tstep : cA; const char* nB = has_next ? (const char*)g.Bt + (size_t)nxt.pn * tstep : cB;
;         for (int t = 0; t < nt; t += 2) {
;             const bool last = (t == nt - 2);
;             const char* a1 = cA + (size_t)(t + 1) * kstep;
;             const char* a2 = last ? nA : cA + (size_t)(t + 2) * kstep; const char* b2 = last ? nB : cB + (size_t)(t + 2) * kstep;
;             const char* a3 = a2 + kstep; const char* b3 = b2 + kstep;
;     ...
; #pragma unroll
;         for (int a = 0; a < 2; ++a)
; #pragma unroll
;             for (int b = 0; b < 2; ++b)
; #pragma unroll
;                 for (int m = 0; m < 4; ++m)
; #pragma unroll
;                     for (int n = 0; n < 2; ++n) acc[a][b][m][n] = (f32x4){0.f, 0.f, 0.f, 0.f};
.LBB0_67:
	s_ashr_i32 s75, s74, 31
	s_lshl_b64 s[76:77], s[74:75], 20
	s_add_u32 s76, s90, s76
	s_addc_u32 s77, s91, s77
	s_and_b64 s[78:79], s[10:11], exec
	s_cselect_b32 s1, s77, s83
	s_cselect_b32 s75, s76, s82
	s_ashr_i32 s73, s72, 31
	s_lshl_b64 s[78:79], s[72:73], 20
	s_add_u32 s78, s58, s78
	s_addc_u32 s79, s59, s79
	s_and_b64 s[86:87], s[10:11], exec
	s_cselect_b32 s73, s79, s85
	s_cselect_b32 s81, s78, s84
	s_add_u32 s82, s82, 0x80080
	s_addc_u32 s83, s83, 0
	s_add_u32 vcc_lo, s84, 0x100
	s_addc_u32 vcc_hi, s85, 0
	s_mov_b32 s29, -2
	v_mov_b64_e32 v[0:1], 0
	v_mov_b64_e32 v[2:3], 0
	v_mov_b64_e32 v[4:5], 0
	v_mov_b64_e32 v[6:7], 0
	v_mov_b64_e32 v[8:9], 0
	v_mov_b64_e32 v[10:11], 0
	v_mov_b64_e32 v[12:13], 0
	v_mov_b64_e32 v[14:15], 0
	v_mov_b64_e32 v[16:17], 0
	v_mov_b64_e32 v[18:19], 0
	v_mov_b64_e32 v[20:21], 0
	v_mov_b64_e32 v[22:23], 0
	v_mov_b64_e32 v[24:25], 0
	v_mov_b64_e32 v[26:27], 0
	v_mov_b64_e32 v[28:29], 0
	v_mov_b64_e32 v[30:31], 0
	v_mov_b64_e32 v[32:33], 0
	v_mov_b64_e32 v[34:35], 0
	v_mov_b64_e32 v[36:37], 0
	v_mov_b64_e32 v[38:39], 0
	v_mov_b64_e32 v[40:41], 0
	v_mov_b64_e32 v[42:43], 0
	v_mov_b64_e32 v[44:45], 0
	v_mov_b64_e32 v[46:47], 0
	v_mov_b64_e32 v[48:49], 0
	v_mov_b64_e32 v[50:51], 0
	v_mov_b64_e32 v[52:53], 0
	v_mov_b64_e32 v[54:55], 0
	v_mov_b64_e32 v[56:57], 0
	v_mov_b64_e32 v[58:59], 0
	v_mov_b64_e32 v[60:61], 0
	v_mov_b64_e32 v[62:63], 0
	v_mov_b64_e32 v[64:65], 0
	v_mov_b64_e32 v[66:67], 0
	v_mov_b64_e32 v[68:69], 0
	v_mov_b64_e32 v[70:71], 0
	v_mov_b64_e32 v[72:73], 0
	v_mov_b64_e32 v[74:75], 0
	v_mov_b64_e32 v[76:77], 0
	v_mov_b64_e32 v[78:79], 0
	v_mov_b64_e32 v[80:81], 0
	v_mov_b64_e32 v[82:83], 0
	v_mov_b64_e32 v[84:85], 0
	v_mov_b64_e32 v[86:87], 0
	v_mov_b64_e32 v[88:89], 0
	v_mov_b64_e32 v[90:91], 0
	v_mov_b64_e32 v[92:93], 0
	v_mov_b64_e32 v[94:95], 0
	v_mov_b64_e32 v[96:97], 0
	v_mov_b64_e32 v[98:99], 0
	v_mov_b64_e32 v[100:101], 0
	v_mov_b64_e32 v[102:103], 0
	v_mov_b64_e32 v[104:105], 0
	v_mov_b64_e32 v[106:107], 0
	v_mov_b64_e32 v[108:109], 0
	v_mov_b64_e32 v[110:111], 0
	v_mov_b64_e32 v[112:113], 0
	v_mov_b64_e32 v[114:115], 0
	v_mov_b64_e32 v[116:117], 0
	v_mov_b64_e32 v[118:119], 0
	v_mov_b64_e32 v[120:121], 0
	v_mov_b64_e32 v[122:123], 0
	v_mov_b64_e32 v[124:125], 0
	v_mov_b64_e32 v[126:127], 0

; template <class Epi, class Sched, bool ALIGN_EPI = false, bool SP2 = false>
; __device__ __forceinline__ void gemm_phase(PG8_LAS unsigned char* lds, const Gemm g, const Sched& S, const Epi& E) {
;     ...
;         const bool has_next = S.next(ui + 1, nxt);
;         const char* nA = has_next ? (const char*)g.A + (size_t)nxt.pm * tstep : cA; const char* nB = has_next ? (const char*)g.Bt + (size_t)nxt.pn * tstep : cB;
;         for (int t = 0; t < nt; t += 2) {
;             const bool last = (t == nt - 2);
;             const char* a1 = cA + (size_t)(t + 1) * kstep;
;             const char* a2 = last ? nA : cA + (size_t)(t + 2) * kstep; const char* b2 = last ? nB : cB + (size_t)(t + 2) * kstep;
;             const char* a3 = a2 + kstep; const char* b3 = b2 + kstep;
;     ...
; #pragma unroll
;         for (int a = 0; a < 2; ++a)
; #pragma unroll
;             for (int b = 0; b < 2; ++b)
; #pragma unroll
;                 for (int m = 0; m < 4; ++m)
; #pragma unroll
;                     for (int n = 0; n < 2; ++n) acc[a][b][m][n] = (f32x4){0.f, 0.f, 0.f, 0.f};
.LBB0_282:
	s_ashr_i32 s59, s58, 31
	s_lshl_b64 s[30:31], s[58:59], 20
	v_cmp_lt_i64_e32 vcc, s[60:61], v[140:141]
	s_add_u32 s60, s38, s30
	s_addc_u32 s61, s39, s31
	s_and_b64 s[30:31], vcc, exec
	s_cselect_b32 s59, s61, s67
	s_cselect_b32 s81, s60, s66
	s_ashr_i32 s57, s56, 31
	s_lshl_b64 s[30:31], s[56:57], 20
	s_add_u32 s62, s52, s30
	s_addc_u32 s63, s53, s31
	s_and_b64 s[30:31], vcc, exec
	s_cselect_b32 s57, s63, s69
	s_cselect_b32 s82, s62, s68
	s_add_u32 s66, s66, 0x80080
	s_addc_u32 s67, s67, 0
	s_add_u32 s83, s68, 0x100
	s_addc_u32 s84, s69, 0
	s_mov_b32 s85, -2
	v_mov_b64_e32 v[0:1], 0
	v_mov_b64_e32 v[2:3], 0
	v_mov_b64_e32 v[4:5], 0
	v_mov_b64_e32 v[6:7], 0
	v_mov_b64_e32 v[8:9], 0
	v_mov_b64_e32 v[10:11], 0
	v_mov_b64_e32 v[12:13], 0
	v_mov_b64_e32 v[14:15], 0
	v_mov_b64_e32 v[16:17], 0
	v_mov_b64_e32 v[18:19], 0
	v_mov_b64_e32 v[20:21], 0
	v_mov_b64_e32 v[22:23], 0
	v_mov_b64_e32 v[24:25], 0
	v_mov_b64_e32 v[26:27], 0
	v_mov_b64_e32 v[28:29], 0
	v_mov_b64_e32 v[30:31], 0
	v_mov_b64_e32 v[32:33], 0
	v_mov_b64_e32 v[34:35], 0
	v_mov_b64_e32 v[36:37], 0
	v_mov_b64_e32 v[38:39], 0
	v_mov_b64_e32 v[40:41], 0
	v_mov_b64_e32 v[42:43], 0
	v_mov_b64_e32 v[44:45], 0
	v_mov_b64_e32 v[46:47], 0
	v_mov_b64_e32 v[48:49], 0
	v_mov_b64_e32 v[50:51], 0
	v_mov_b64_e32 v[52:53], 0
	v_mov_b64_e32 v[54:55], 0
	v_mov_b64_e32 v[56:57], 0
	v_mov_b64_e32 v[58:59], 0
	v_mov_b64_e32 v[60:61], 0
	v_mov_b64_e32 v[62:63], 0
	v_mov_b64_e32 v[64:65], 0
	v_mov_b64_e32 v[66:67], 0
	v_mov_b64_e32 v[68:69], 0
	v_mov_b64_e32 v[70:71], 0
	v_mov_b64_e32 v[72:73], 0
	v_mov_b64_e32 v[74:75], 0
	v_mov_b64_e32 v[76:77], 0
	v_mov_b64_e32 v[78:79], 0
	v_mov_b64_e32 v[80:81], 0
	v_mov_b64_e32 v[82:83], 0
	v_mov_b64_e32 v[84:85], 0
	v_mov_b64_e32 v[86:87], 0
	v_mov_b64_e32 v[88:89], 0
	v_mov_b64_e32 v[90:91], 0
	v_mov_b64_e32 v[92:93], 0
	v_mov_b64_e32 v[94:95], 0
	v_mov_b64_e32 v[96:97], 0
	v_mov_b64_e32 v[98:99], 0
	v_mov_b64_e32 v[100:101], 0
	v_mov_b64_e32 v[102:103], 0
	v_mov_b64_e32 v[104:105], 0
	v_mov_b64_e32 v[106:107], 0
	v_mov_b64_e32 v[108:109], 0
	v_mov_b64_e32 v[110:111], 0
	v_mov_b64_e32 v[112:113], 0
	v_mov_b64_e32 v[114:115], 0
	v_mov_b64_e32 v[116:117], 0
	v_mov_b64_e32 v[118:119], 0
	v_mov_b64_e32 v[120:121], 0
	v_mov_b64_e32 v[122:123], 0
	v_mov_b64_e32 v[124:125], 0
	v_mov_b64_e32 v[126:127], 0

; template <class Epi, class Sched, bool ALIGN_EPI = false, bool SP2 = false>
; __device__ __forceinline__ void gemm_phase(PG8_LAS unsigned char* lds, const Gemm g, const Sched& S, const Epi& E) {
;     ...
;         const bool has_next = S.next(ui + 1, nxt);
;         const char* nA = has_next ? (const char*)g.A + (size_t)nxt.pm * tstep : cA; const char* nB = has_next ? (const char*)g.Bt + (size_t)nxt.pn * tstep : cB;
;         for (int t = 0; t < nt; t += 2) {
;             const bool last = (t == nt - 2);
;             const char* a1 = cA + (size_t)(t + 1) * kstep;
;             const char* a2 = last ? nA : cA + (size_t)(t + 2) * kstep; const char* b2 = last ? nB : cB + (size_t)(t + 2) * kstep;
;             const char* a3 = a2 + kstep; const char* b3 = b2 + kstep;
;     ...
; #pragma unroll
;         for (int a = 0; a < 2; ++a)
; #pragma unroll
;             for (int b = 0; b < 2; ++b)
; #pragma unroll
;                 for (int m = 0; m < 4; ++m)
; #pragma unroll
;                     for (int n = 0; n < 2; ++n) acc[a][b][m][n] = (f32x4){0.f, 0.f, 0.f, 0.f};
.LBB0_403:
	s_ashr_i32 s65, s64, 31
	s_lshl_b64 s[30:31], s[64:65], 20
	s_add_u32 s66, s90, s30
	s_addc_u32 s67, s91, s31
	s_and_b64 s[30:31], s[8:9], exec
	s_cselect_b32 s1, s67, s11
	s_cselect_b32 s22, s66, s10
	s_ashr_i32 s63, s62, 31
	s_lshl_b64 s[30:31], s[62:63], 20
	s_add_u32 s68, s34, s30
	s_addc_u32 s69, s35, s31
	s_and_b64 s[30:31], s[8:9], exec
	s_cselect_b32 s33, s69, s73
	s_cselect_b32 s46, s68, s72
	s_add_u32 s10, s10, 0x80080
	s_addc_u32 s11, s11, 0
	s_add_u32 s47, s72, 0x100
	s_addc_u32 s63, s73, 0
	s_mov_b32 s65, -2
	v_mov_b64_e32 v[0:1], 0
	v_mov_b64_e32 v[2:3], 0
	v_mov_b64_e32 v[4:5], 0
	v_mov_b64_e32 v[6:7], 0
	v_mov_b64_e32 v[8:9], 0
	v_mov_b64_e32 v[10:11], 0
	v_mov_b64_e32 v[12:13], 0
	v_mov_b64_e32 v[14:15], 0
	v_mov_b64_e32 v[16:17], 0
	v_mov_b64_e32 v[18:19], 0
	v_mov_b64_e32 v[20:21], 0
	v_mov_b64_e32 v[22:23], 0
	v_mov_b64_e32 v[24:25], 0
	v_mov_b64_e32 v[26:27], 0
	v_mov_b64_e32 v[28:29], 0
	v_mov_b64_e32 v[30:31], 0
	v_mov_b64_e32 v[32:33], 0
	v_mov_b64_e32 v[34:35], 0
	v_mov_b64_e32 v[36:37], 0
	v_mov_b64_e32 v[38:39], 0
	v_mov_b64_e32 v[40:41], 0
	v_mov_b64_e32 v[42:43], 0
	v_mov_b64_e32 v[44:45], 0
	v_mov_b64_e32 v[46:47], 0
	v_mov_b64_e32 v[48:49], 0
	v_mov_b64_e32 v[50:51], 0
	v_mov_b64_e32 v[52:53], 0
	v_mov_b64_e32 v[54:55], 0
	v_mov_b64_e32 v[56:57], 0
	v_mov_b64_e32 v[58:59], 0
	v_mov_b64_e32 v[60:61], 0
	v_mov_b64_e32 v[62:63], 0
	v_mov_b64_e32 v[64:65], 0
	v_mov_b64_e32 v[66:67], 0
	v_mov_b64_e32 v[68:69], 0
	v_mov_b64_e32 v[70:71], 0
	v_mov_b64_e32 v[72:73], 0
	v_mov_b64_e32 v[74:75], 0
	v_mov_b64_e32 v[76:77], 0
	v_mov_b64_e32 v[78:79], 0
	v_mov_b64_e32 v[80:81], 0
	v_mov_b64_e32 v[82:83], 0
	v_mov_b64_e32 v[84:85], 0
	v_mov_b64_e32 v[86:87], 0
	v_mov_b64_e32 v[88:89], 0
	v_mov_b64_e32 v[90:91], 0
	v_mov_b64_e32 v[92:93], 0
	v_mov_b64_e32 v[94:95], 0
	v_mov_b64_e32 v[96:97], 0
	v_mov_b64_e32 v[98:99], 0
	v_mov_b64_e32 v[100:101], 0
	v_mov_b64_e32 v[102:103], 0
	v_mov_b64_e32 v[104:105], 0
	v_mov_b64_e32 v[106:107], 0
	v_mov_b64_e32 v[108:109], 0
	v_mov_b64_e32 v[110:111], 0
	v_mov_b64_e32 v[114:115], 0
	v_mov_b64_e32 v[116:117], 0
	v_mov_b64_e32 v[122:123], 0
	v_mov_b64_e32 v[124:125], 0
	v_mov_b64_e32 v[158:159], 0
	v_mov_b64_e32 v[160:161], 0
	v_mov_b64_e32 v[162:163], 0
	v_mov_b64_e32 v[164:165], 0

; #define PG8_LAS __attribute__((address_space(3)))
;     __device__ __forceinline__ void operator()(const f32x4 (&acc)[2][2][4][2], const Unit& u, int wr, int wc, int fr, int fq) const {
;     ...
;         if (fr >= 14) {
; #pragma unroll
;             for (int ai = 0; ai < 2; ++ai)
; #pragma unroll
;                 for (int bj = 0; bj < 2; ++bj)
; #pragma unroll
;                     for (int n = 0; n < 2; ++n) *(PG8_LAS f32x4*)(xch + ((ai * 2 + wr) * 4 + wc) * 128 + (fr - 14) * 64 + (bj * 2 + n) * 16 + fq * 4) = acc[ai][bj][3][n];
;             if (wr == 1) {
; #pragma unroll
;                 for (int bj = 0; bj < 2; ++bj)
; #pragma unroll
;                     for (int n = 0; n < 2; ++n) *(f32x4*)(raw + ((size_t)u.pm * 4 + 2 + (fr - 14)) * upw + u.pn * BM + bj * HALF + wc * 32 + 8 * fq + 4 * n) = acc[1][bj][3][n];
;             }
;         }
;         if (fr < 2 && wr == 0) {
; #pragma unroll
;             for (int bj = 0; bj < 2; ++bj)
; #pragma unroll
;                 for (int n = 0; n < 2; ++n) *(f32x4*)(raw + ((size_t)u.pm * 4 + fr) * upw + u.pn * BM + bj * HALF + wc * 32 + 8 * fq + 4 * n) = acc[0][bj][0][n];
;         }
;         asm volatile("s_waitcnt lgkmcnt(0)" ::: "memory"); __builtin_amdgcn_s_barrier(); asm volatile("" ::: "memory");
;         u32x2 keep[2][4];
; #pragma unroll
;         for (int n = 0; n < 2; ++n) {
;             const int ch0 = u.pn * HALF + wc * 32 + 8 * fq + 4 * n;
;             f32x4 w0[2], w1[2], w2[2], bb[2];
; #pragma unroll
;             for (int bj = 0; bj < 2; ++bj) { w0[bj] = *(const f32x4*)(cw + bj * dff + ch0); w1[bj] = *(const f32x4*)(cw + upw + bj * dff + ch0); w2[bj] = *(const f32x4*)(cw + 2 * upw + bj * dff + ch0); bb[bj] = *(const f32x4*)(cb + bj * dff + ch0); }
.LBB0_407:
	s_lshl_b32 s1, s0, 9
	s_lshl_b32 s22, s81, 7
	s_add_i32 s1, s1, s22
	v_lshl_add_u32 v112, v192, 2, s1
	v_add_u32_e32 v113, 0x5800, v112
	global_load_dwordx4 v[126:129], v112, s[26:27]
	global_load_dwordx4 v[130:133], v113, s[26:27]
	global_load_dwordx4 v[134:137], v112, s[58:59]
	global_load_dwordx4 v[138:141], v113, s[58:59]
	global_load_dwordx4 v[142:145], v112, s[60:61]
	global_load_dwordx4 v[146:149], v113, s[60:61]
	global_load_dwordx4 v[150:153], v112, s[44:45]
	global_load_dwordx4 v[154:157], v113, s[44:45]
	v_cmp_eq_u32_e64 s[10:11], 15, v190
	v_add_u32_e32 v205, v212, v191
	v_add_u32_e32 v205, 0xfffff100, v205
	s_mul_i32 s1, s70, 0x2c000
	s_lshl_b32 s22, s0, 10
	s_add_i32 s1, s1, s22
	s_lshl_b32 s22, s81, 7
	s_add_i32 s1, s1, s22
	s_add_u32 s46, s20, s1
	s_addc_u32 s47, s21, 0
	v_lshl_add_u32 v204, v192, 2, 0
	s_and_saveexec_b64 s[72:73], s[10:11]
	s_cbranch_execz .Lffn_a1
	ds_write_b128 v205, v[108:111]
	ds_write_b128 v205, v[44:47] offset:64
	ds_write_b128 v205, v[100:103] offset:128
	ds_write_b128 v205, v[36:39] offset:192
	ds_write_b128 v205, v[104:107] offset:256
	ds_write_b128 v205, v[40:43] offset:320
	ds_write_b128 v205, v[96:99] offset:384
	ds_write_b128 v205, v[32:35] offset:448
	ds_write_b128 v205, v[76:79] offset:4096
	ds_write_b128 v205, v[12:15] offset:4160
	ds_write_b128 v205, v[68:71] offset:4224
	ds_write_b128 v205, v[4:7] offset:4288
	ds_write_b128 v205, v[72:75] offset:4352
	ds_write_b128 v205, v[8:11] offset:4416
	ds_write_b128 v205, v[64:67] offset:4480
	ds_write_b128 v205, v[0:3] offset:4544
	s_and_b64 vcc, exec, s[36:37]
	s_cbranch_vccz .Lffn_a1
	s_add_u32 s46, s46, 0x16000
	s_addc_u32 s47, s47, 0
	global_store_dwordx4 v204, v[76:79], s[46:47]
	global_store_dwordx4 v204, v[12:15], s[46:47] offset:16
	global_store_dwordx4 v204, v[68:71], s[46:47] offset:512
	global_store_dwordx4 v204, v[4:7], s[46:47] offset:528
	s_add_u32 s46, s46, 0xb000
	s_addc_u32 s47, s47, 0
	global_store_dwordx4 v204, v[72:75], s[46:47]
	global_store_dwordx4 v204, v[8:11], s[46:47] offset:16
	global_store_dwordx4 v204, v[64:67], s[46:47] offset:512
	global_store_dwordx4 v204, v[0:3], s[46:47] offset:528

; #define PG8_LAS __attribute__((address_space(3)))
;     __device__ __forceinline__ void operator()(const f32x4 (&acc)[2][2][4][2], const Unit& u, int wr, int wc, int fr, int fq) const {
;     ...
;         asm volatile("s_waitcnt lgkmcnt(0)" ::: "memory"); __builtin_amdgcn_s_barrier(); asm volatile("" ::: "memory");
;         u32x2 keep[2][4];
; #pragma unroll
;         for (int n = 0; n < 2; ++n) {
;             const int ch0 = u.pn * HALF + wc * 32 + 8 * fq + 4 * n;
;             f32x4 w0[2], w1[2], w2[2], bb[2];
; #pragma unroll
;             for (int bj = 0; bj < 2; ++bj) { w0[bj] = *(const f32x4*)(cw + bj * dff + ch0); w1[bj] = *(const f32x4*)(cw + upw + bj * dff + ch0); w2[bj] = *(const f32x4*)(cw + 2 * upw + bj * dff + ch0); bb[bj] = *(const f32x4*)(cb + bj * dff + ch0); }
; #pragma unroll
;             for (int ai = 0; ai < 2; ++ai) {
;                 f32x4 h15[2], h14[2];
;                 if (wr == 1 || ai == 1) { const int src = (wr == 1) ? (ai * 2 + 0) : (0 * 2 + 1);
; #pragma unroll
;                     for (int bj = 0; bj < 2; ++bj) { h14[bj] = *(const PG8_LAS f32x4*)(xch + (src * 4 + wc) * 128 + 0 * 64 + (bj * 2 + n) * 16 + fq * 4); h15[bj] = *(const PG8_LAS f32x4*)(xch + (src * 4 + wc) * 128 + 1 * 64 + (bj * 2 + n) * 16 + fq * 4); }
;                 } else {
; #pragma unroll
;                     for (int bj = 0; bj < 2; ++bj) { h14[bj] = (f32x4){0.f, 0.f, 0.f, 0.f}; h15[bj] = (f32x4){0.f, 0.f, 0.f, 0.f}; } }
; #pragma unroll
;                 for (int m = 0; m < 4; ++m) {
;                     float val[2][4];
; #pragma unroll
;                     for (int bj = 0; bj < 2; ++bj)
; #pragma unroll
;                         for (int jj = 0; jj < 4; ++jj) {
;                             const float cur = acc[ai][bj][m][n][jj];
;                             float o1, o2;
;                             if (m > 0) { const float pv = acc[ai][bj][m > 0 ? m - 1 : 0][n][jj]; o1 = dppf<0x121>(0.f, pv); o2 = dppf<0x122>(0.f, pv); }
;                             else { o1 = h15[bj][jj]; o2 = (fr == 0) ? h14[bj][jj] : h15[bj][jj]; }
;                             const float p1 = dppf<0x111>(o1, cur), p2 = dppf<0x112>(o2, cur);
;                             val[bj][jj] = w2[bj][jj] * cur + w1[bj][jj] * p1 + w0[bj][jj] * p2 + bb[bj][jj];
;                         }
;                     float y[4];
; #pragma unroll
.Lffn_a2:
	s_or_b64 exec, exec, s[72:73]
	s_mul_i32 s1, s70, 0x2c0000
	s_lshl_b32 s22, s0, 8
	s_add_i32 s1, s1, s22
	s_lshl_b32 s22, s81, 6
	s_add_i32 s1, s1, s22
	s_add_u32 s30, s12, s1
	s_addc_u32 s31, s13, 0
	s_and_b64 vcc, exec, s[36:37]
	s_cbranch_vccz .Lffn_b0
	s_add_u32 s30, s30, 0xb0000
	s_addc_u32 s31, s31, 0
.Lffn_b0:
	v_mul_u32_u24_e32 v188, 0xb000, v190
	v_add_u32_e32 v188, v212, v188
	s_mov_b32 s71, 0xbfb8aa3b
	s_mov_b32 s22, 0xbfb8aa3b
	s_mov_b32 s23, 0xbfb8aa3b
	s_mov_b32 s46, 0x3f800000
	s_mov_b32 s47, 0x3f800000
	s_waitcnt lgkmcnt(0)
	s_barrier
	v_mov_b32_e32 v166, 0
	v_mov_b32_e32 v174, 0
	v_mov_b32_e32 v167, 0
	v_mov_b32_e32 v175, 0
	v_mov_b32_e32 v168, 0
	v_mov_b32_e32 v176, 0
	v_mov_b32_e32 v169, 0
	v_mov_b32_e32 v177, 0
	v_mov_b32_e32 v170, 0
	v_mov_b32_e32 v118, 0
	v_mov_b32_e32 v171, 0
	v_mov_b32_e32 v119, 0
	v_mov_b32_e32 v172, 0
	v_mov_b32_e32 v120, 0
	v_mov_b32_e32 v173, 0
	v_mov_b32_e32 v121, 0
	s_and_b64 vcc, exec, s[36:37]
	s_cbranch_vccz .Lffn_h00
	ds_read_b128 v[166:169], v214
	ds_read_b128 v[174:177], v214 offset:256
	ds_read_b128 v[170:173], v214 offset:128
	ds_read_b128 v[118:121], v214 offset:384
.Lffn_h00:
	s_waitcnt vmcnt(8) lgkmcnt(0)
	v_mov_b32_dpp v174, v104 row_shr:1 row_mask:0xf bank_mask:0xf
	v_mov_b32_dpp v175, v105 row_shr:1 row_mask:0xf bank_mask:0xf
	v_mov_b32_dpp v176, v106 row_shr:1 row_mask:0xf bank_mask:0xf
	v_mov_b32_dpp v177, v107 row_shr:1 row_mask:0xf bank_mask:0xf
	v_mov_b32_dpp v166, v108 row_shr:1 row_mask:0xf bank_mask:0xf
	v_mov_b32_dpp v167, v109 row_shr:1 row_mask:0xf bank_mask:0xf
	v_mov_b32_dpp v168, v110 row_shr:1 row_mask:0xf bank_mask:0xf
	v_mov_b32_dpp v169, v111 row_shr:1 row_mask:0xf bank_mask:0xf
	v_pk_fma_f32 v[104:105], v[142:143], v[104:105], v[150:151]
	v_pk_fma_f32 v[106:107], v[144:145], v[106:107], v[152:153]
	v_pk_fma_f32 v[104:105], v[134:135], v[108:109], v[104:105]
	v_pk_fma_f32 v[106:107], v[136:137], v[110:111], v[106:107]
	v_pk_fma_f32 v[104:105], v[126:127], v[122:123], v[104:105]
	v_pk_fma_f32 v[106:107], v[128:129], v[124:125], v[106:107]
	v_pk_fma_f32 v[108:109], v[142:143], v[108:109], v[150:151]
	v_pk_fma_f32 v[110:111], v[144:145], v[110:111], v[152:153]
	v_pk_fma_f32 v[108:109], v[134:135], v[122:123], v[108:109]
	v_pk_fma_f32 v[110:111], v[136:137], v[124:125], v[110:111]
	v_pk_fma_f32 v[108:109], v[126:127], v[162:163], v[108:109]
	v_pk_fma_f32 v[110:111], v[128:129], v[164:165], v[110:111]
	v_pk_fma_f32 v[122:123], v[142:143], v[122:123], v[150:151]
	v_pk_fma_f32 v[124:125], v[144:145], v[124:125], v[152:153]
	v_pk_fma_f32 v[122:123], v[134:135], v[162:163], v[122:123]
	v_pk_fma_f32 v[124:125], v[136:137], v[164:165], v[124:125]
	v_pk_fma_f32 v[122:123], v[126:127], v[174:175], v[122:123]
	v_pk_fma_f32 v[124:125], v[128:129], v[176:177], v[124:125]
	v_pk_fma_f32 v[162:163], v[142:143], v[162:163], v[150:151]
	v_pk_fma_f32 v[164:165], v[144:145], v[164:165], v[152:153]
	v_pk_fma_f32 v[162:163], v[134:135], v[174:175], v[162:163]
	v_pk_fma_f32 v[164:165], v[136:137], v[176:177], v[164:165]
	v_pk_fma_f32 v[162:163], v[126:127], v[166:167], v[162:163]
	v_pk_fma_f32 v[164:165], v[128:129], v[168:169], v[164:165]
	v_mov_b32_dpp v118, v96 row_shr:1 row_mask:0xf bank_mask:0xf
	v_mov_b32_dpp v119, v97 row_shr:1 row_mask:0xf bank_mask:0xf
	v_mov_b32_dpp v120, v98 row_shr:1 row_mask:0xf bank_mask:0xf
	v_mov_b32_dpp v121, v99 row_shr:1 row_mask:0xf bank_mask:0xf
	v_mov_b32_dpp v170, v100 row_shr:1 row_mask:0xf bank_mask:0xf
	v_mov_b32_dpp v171, v101 row_shr:1 row_mask:0xf bank_mask:0xf
	v_mov_b32_dpp v172, v102 row_shr:1 row_mask:0xf bank_mask:0xf
	v_mov_b32_dpp v173, v103 row_shr:1 row_mask:0xf bank_mask:0xf
	v_pk_fma_f32 v[96:97], v[146:147], v[96:97], v[154:155]
	v_pk_fma_f32 v[98:99], v[148:149], v[98:99], v[156:157]
	v_pk_fma_f32 v[96:97], v[138:139], v[100:101], v[96:97]
	v_pk_fma_f32 v[98:99], v[140:141], v[102:103], v[98:99]
	v_pk_fma_f32 v[96:97], v[130:131], v[114:115], v[96:97]
	v_pk_fma_f32 v[98:99], v[132:133], v[116:117], v[98:99]
	v_pk_fma_f32 v[100:101], v[146:147], v[100:101], v[154:155]
	v_pk_fma_f32 v[102:103], v[148:149], v[102:103], v[156:157]
	v_pk_fma_f32 v[100:101], v[138:139], v[114:115], v[100:101]
	v_pk_fma_f32 v[102:103], v[140:141], v[116:117], v[102:103]
	v_pk_fma_f32 v[100:101], v[130:131], v[158:159], v[100:101]
	v_pk_fma_f32 v[102:103], v[132:133], v[160:161], v[102:103]
	v_pk_fma_f32 v[114:115], v[146:147], v[114:115], v[154:155]
	v_pk_fma_f32 v[116:117], v[148:149], v[116:117], v[156:157]
	v_pk_fma_f32 v[114:115], v[138:139], v[158:159], v[114:115]
	v_pk_fma_f32 v[116:117], v[140:141], v[160:161], v[116:117]
	v_pk_fma_f32 v[114:115], v[130:131], v[118:119], v[114:115]
	v_pk_fma_f32 v[116:117], v[132:133], v[120:121], v[116:117]
	v_pk_fma_f32 v[158:159], v[146:147], v[158:159], v[154:155]
	v_pk_fma_f32 v[160:161], v[148:149], v[160:161], v[156:157]
	v_pk_fma_f32 v[158:159], v[138:139], v[118:119], v[158:159]
	v_pk_fma_f32 v[160:161], v[140:141], v[120:121], v[160:161]
	v_pk_fma_f32 v[158:159], v[130:131], v[170:171], v[158:159]
	v_pk_fma_f32 v[160:161], v[132:133], v[172:173], v[160:161]
	v_pk_mul_f32 v[208:209], v[158:159], s[22:23]
	v_pk_mul_f32 v[210:211], v[160:161], s[22:23]
	v_exp_f32_e32 v208, v208
	v_exp_f32_e32 v209, v209
	v_exp_f32_e32 v210, v210
	v_exp_f32_e32 v211, v211
	v_pk_mul_f32 v[162:163], v[162:163], v[158:159]
	v_pk_mul_f32 v[164:165], v[164:165], v[160:161]
	v_pk_add_f32 v[208:209], v[208:209], s[46:47]
	v_pk_add_f32 v[210:211], v[210:211], s[46:47]
	v_rcp_f32_e32 v208, v208
	v_rcp_f32_e32 v209, v209
	v_rcp_f32_e32 v210, v210
	v_rcp_f32_e32 v211, v211
	s_nop 0
	v_pk_mul_f32 v[162:163], v[162:163], v[208:209]
; #define PG8_LAS __attribute__((address_space(3)))
; __device__ __forceinline__ unsigned cvt_pk_bf16(float lo, float hi) { unsigned r; asm volatile("v_cvt_pk_bf16_f32 %0, %1, %2" : "=v"(r) : "v"(lo), "v"(hi)); return r; }
;     __device__ __forceinline__ void operator()(const f32x4 (&acc)[2][2][4][2], const Unit& u, int wr, int wc, int fr, int fq) const {
;     ...
;             for (int ai = 0; ai < 2; ++ai) {
;                 f32x4 h15[2], h14[2];
;                 if (wr == 1 || ai == 1) { const int src = (wr == 1) ? (ai * 2 + 0) : (0 * 2 + 1);
; #pragma unroll
;                     for (int bj = 0; bj < 2; ++bj) { h14[bj] = *(const PG8_LAS f32x4*)(xch + (src * 4 + wc) * 128 + 0 * 64 + (bj * 2 + n) * 16 + fq * 4); h15[bj] = *(const PG8_LAS f32x4*)(xch + (src * 4 + wc) * 128 + 1 * 64 + (bj * 2 + n) * 16 + fq * 4); }
;                 } else {
; #pragma unroll
;                     for (int bj = 0; bj < 2; ++bj) { h14[bj] = (f32x4){0.f, 0.f, 0.f, 0.f}; h15[bj] = (f32x4){0.f, 0.f, 0.f, 0.f}; } }
; #pragma unroll
;                 for (int m = 0; m < 4; ++m) {
;                     float val[2][4];
; #pragma unroll
;                     for (int bj = 0; bj < 2; ++bj)
; #pragma unroll
;                         for (int jj = 0; jj < 4; ++jj) {
;                             const float cur = acc[ai][bj][m][n][jj];
;                             float o1, o2;
;                             if (m > 0) { const float pv = acc[ai][bj][m > 0 ? m - 1 : 0][n][jj]; o1 = dppf<0x121>(0.f, pv); o2 = dppf<0x122>(0.f, pv); }
;                             else { o1 = h15[bj][jj]; o2 = (fr == 0) ? h14[bj][jj] : h15[bj][jj]; }
;                             const float p1 = dppf<0x111>(o1, cur), p2 = dppf<0x112>(o2, cur);
;                             val[bj][jj] = w2[bj][jj] * cur + w1[bj][jj] * p1 + w0[bj][jj] * p2 + bb[bj][jj];
;                         }
;                     float y[4];
; #pragma unroll
;                     for (int jj = 0; jj < 4; ++jj) { const float g = val[1][jj]; y[jj] = val[0][jj] * g * __builtin_amdgcn_rcpf(1.0f + __builtin_amdgcn_exp2f(-1.4426950408889634f * g)); }
;                     u32x2 w; w.x = cvt_pk_bf16(y[0], y[1]); w.y = cvt_pk_bf16(y[2], y[3]);
	v_pk_mul_f32 v[164:165], v[164:165], v[210:211]
	v_cvt_pk_bf16_f32 v158, v162, v163
	v_cvt_pk_bf16_f32 v159, v164, v165
	v_pk_mul_f32 v[208:209], v[114:115], s[22:23]
	v_pk_mul_f32 v[210:211], v[116:117], s[22:23]
	v_exp_f32_e32 v208, v208
	v_exp_f32_e32 v209, v209
	v_exp_f32_e32 v210, v210
	v_exp_f32_e32 v211, v211
	v_pk_mul_f32 v[122:123], v[122:123], v[114:115]
	v_pk_mul_f32 v[124:125], v[124:125], v[116:117]
	v_pk_add_f32 v[208:209], v[208:209], s[46:47]
	v_pk_add_f32 v[210:211], v[210:211], s[46:47]
	v_rcp_f32_e32 v208, v208
	v_rcp_f32_e32 v209, v209
	v_rcp_f32_e32 v210, v210
	v_rcp_f32_e32 v211, v211
	s_nop 0
	v_pk_mul_f32 v[122:123], v[122:123], v[208:209]
	v_pk_mul_f32 v[124:125], v[124:125], v[210:211]
	v_cvt_pk_bf16_f32 v114, v122, v123
	v_cvt_pk_bf16_f32 v115, v124, v125
	v_pk_mul_f32 v[208:209], v[100:101], s[22:23]
	v_pk_mul_f32 v[210:211], v[102:103], s[22:23]
	v_exp_f32_e32 v208, v208
	v_exp_f32_e32 v209, v209
	v_exp_f32_e32 v210, v210
	v_exp_f32_e32 v211, v211
	v_pk_mul_f32 v[108:109], v[108:109], v[100:101]
	v_pk_mul_f32 v[110:111], v[110:111], v[102:103]
	v_pk_add_f32 v[208:209], v[208:209], s[46:47]
	v_pk_add_f32 v[210:211], v[210:211], s[46:47]
	v_rcp_f32_e32 v208, v208
	v_rcp_f32_e32 v209, v209
	v_rcp_f32_e32 v210, v210
	v_rcp_f32_e32 v211, v211
	s_nop 0
	v_pk_mul_f32 v[108:109], v[108:109], v[208:209]
	v_pk_mul_f32 v[110:111], v[110:111], v[210:211]
	v_cvt_pk_bf16_f32 v100, v108, v109
	v_cvt_pk_bf16_f32 v101, v110, v111
	v_pk_mul_f32 v[208:209], v[96:97], s[22:23]
	v_pk_mul_f32 v[210:211], v[98:99], s[22:23]
	v_exp_f32_e32 v208, v208
	v_exp_f32_e32 v209, v209
	v_exp_f32_e32 v210, v210
	v_exp_f32_e32 v211, v211
	v_pk_mul_f32 v[104:105], v[104:105], v[96:97]
	v_pk_mul_f32 v[106:107], v[106:107], v[98:99]
	v_pk_add_f32 v[208:209], v[208:209], s[46:47]
	v_pk_add_f32 v[210:211], v[210:211], s[46:47]
	v_rcp_f32_e32 v208, v208
	v_rcp_f32_e32 v209, v209
	v_rcp_f32_e32 v210, v210
	v_rcp_f32_e32 v211, v211
	s_nop 0
	v_pk_mul_f32 v[104:105], v[104:105], v[208:209]
	v_pk_mul_f32 v[106:107], v[106:107], v[210:211]
	v_cvt_pk_bf16_f32 v96, v104, v105
	v_cvt_pk_bf16_f32 v97, v106, v107
	s_mov_b32 s1, 0x800
	s_and_b64 vcc, exec, s[36:37]
	s_cbranch_vccz .Lffn_hs
	s_mov_b32 s1, 0x1000
.Lffn_hs:
	v_add_u32_e32 v206, s1, v214
	ds_read_b128 v[166:169], v206
	ds_read_b128 v[174:177], v206 offset:256
	ds_read_b128 v[170:173], v206 offset:128
	ds_read_b128 v[118:121], v206 offset:384
	s_waitcnt lgkmcnt(0)
	v_mov_b32_dpp v174, v72 row_shr:1 row_mask:0xf bank_mask:0xf
	v_mov_b32_dpp v175, v73 row_shr:1 row_mask:0xf bank_mask:0xf
	v_mov_b32_dpp v176, v74 row_shr:1 row_mask:0xf bank_mask:0xf
	v_mov_b32_dpp v177, v75 row_shr:1 row_mask:0xf bank_mask:0xf
	v_mov_b32_dpp v166, v76 row_shr:1 row_mask:0xf bank_mask:0xf
	v_mov_b32_dpp v167, v77 row_shr:1 row_mask:0xf bank_mask:0xf
	v_mov_b32_dpp v168, v78 row_shr:1 row_mask:0xf bank_mask:0xf
	v_mov_b32_dpp v169, v79 row_shr:1 row_mask:0xf bank_mask:0xf
	v_pk_fma_f32 v[72:73], v[142:143], v[72:73], v[150:151]
	v_pk_fma_f32 v[74:75], v[144:145], v[74:75], v[152:153]
	v_pk_fma_f32 v[72:73], v[134:135], v[76:77], v[72:73]
	v_pk_fma_f32 v[74:75], v[136:137], v[78:79], v[74:75]
	v_pk_fma_f32 v[72:73], v[126:127], v[84:85], v[72:73]
	v_pk_fma_f32 v[74:75], v[128:129], v[86:87], v[74:75]
	v_pk_fma_f32 v[76:77], v[142:143], v[76:77], v[150:151]
	v_pk_fma_f32 v[78:79], v[144:145], v[78:79], v[152:153]
	v_pk_fma_f32 v[76:77], v[134:135], v[84:85], v[76:77]
	v_pk_fma_f32 v[78:79], v[136:137], v[86:87], v[78:79]
	v_pk_fma_f32 v[76:77], v[126:127], v[92:93], v[76:77]
	v_pk_fma_f32 v[78:79], v[128:129], v[94:95], v[78:79]
	v_pk_fma_f32 v[84:85], v[142:143], v[84:85], v[150:151]
	v_pk_fma_f32 v[86:87], v[144:145], v[86:87], v[152:153]
	v_pk_fma_f32 v[84:85], v[134:135], v[92:93], v[84:85]
	v_pk_fma_f32 v[86:87], v[136:137], v[94:95], v[86:87]
	v_pk_fma_f32 v[84:85], v[126:127], v[174:175], v[84:85]
	v_pk_fma_f32 v[86:87], v[128:129], v[176:177], v[86:87]
	v_pk_fma_f32 v[92:93], v[142:143], v[92:93], v[150:151]
	v_pk_fma_f32 v[94:95], v[144:145], v[94:95], v[152:153]
	v_pk_fma_f32 v[92:93], v[134:135], v[174:175], v[92:93]
	v_pk_fma_f32 v[94:95], v[136:137], v[176:177], v[94:95]
	v_pk_fma_f32 v[92:93], v[126:127], v[166:167], v[92:93]
	v_pk_fma_f32 v[94:95], v[128:129], v[168:169], v[94:95]
	v_mov_b32_dpp v118, v64 row_shr:1 row_mask:0xf bank_mask:0xf
	v_mov_b32_dpp v119, v65 row_shr:1 row_mask:0xf bank_mask:0xf
	v_mov_b32_dpp v120, v66 row_shr:1 row_mask:0xf bank_mask:0xf
	v_mov_b32_dpp v121, v67 row_shr:1 row_mask:0xf bank_mask:0xf
	v_mov_b32_dpp v170, v68 row_shr:1 row_mask:0xf bank_mask:0xf
	v_mov_b32_dpp v171, v69 row_shr:1 row_mask:0xf bank_mask:0xf
	v_mov_b32_dpp v172, v70 row_shr:1 row_mask:0xf bank_mask:0xf
	v_mov_b32_dpp v173, v71 row_shr:1 row_mask:0xf bank_mask:0xf
	v_pk_fma_f32 v[64:65], v[146:147], v[64:65], v[154:155]
	v_pk_fma_f32 v[66:67], v[148:149], v[66:67], v[156:157]
	v_pk_fma_f32 v[64:65], v[138:139], v[68:69], v[64:65]
	v_pk_fma_f32 v[66:67], v[140:141], v[70:71], v[66:67]
	v_pk_fma_f32 v[64:65], v[130:131], v[80:81], v[64:65]
	v_pk_fma_f32 v[66:67], v[132:133], v[82:83], v[66:67]
	v_pk_fma_f32 v[68:69], v[146:147], v[68:69], v[154:155]
	v_pk_fma_f32 v[70:71], v[148:149], v[70:71], v[156:157]
	v_pk_fma_f32 v[68:69], v[138:139], v[80:81], v[68:69]
	v_pk_fma_f32 v[70:71], v[140:141], v[82:83], v[70:71]
	v_pk_fma_f32 v[68:69], v[130:131], v[88:89], v[68:69]
	v_pk_fma_f32 v[70:71], v[132:133], v[90:91], v[70:71]
	v_pk_fma_f32 v[80:81], v[146:147], v[80:81], v[154:155]
	v_pk_fma_f32 v[82:83], v[148:149], v[82:83], v[156:157]
	v_pk_fma_f32 v[80:81], v[138:139], v[88:89], v[80:81]
; #define PG8_LAS __attribute__((address_space(3)))
;     __device__ __forceinline__ void operator()(const f32x4 (&acc)[2][2][4][2], const Unit& u, int wr, int wc, int fr, int fq) const {
;     ...
;             for (int bj = 0; bj < 2; ++bj) { w0[bj] = *(const f32x4*)(cw + bj * dff + ch0); w1[bj] = *(const f32x4*)(cw + upw + bj * dff + ch0); w2[bj] = *(const f32x4*)(cw + 2 * upw + bj * dff + ch0); bb[bj] = *(const f32x4*)(cb + bj * dff + ch0); }
; #pragma unroll
;             for (int ai = 0; ai < 2; ++ai) {
;                 f32x4 h15[2], h14[2];
;                 if (wr == 1 || ai == 1) { const int src = (wr == 1) ? (ai * 2 + 0) : (0 * 2 + 1);
; #pragma unroll
;                     for (int bj = 0; bj < 2; ++bj) { h14[bj] = *(const PG8_LAS f32x4*)(xch + (src * 4 + wc) * 128 + 0 * 64 + (bj * 2 + n) * 16 + fq * 4); h15[bj] = *(const PG8_LAS f32x4*)(xch + (src * 4 + wc) * 128 + 1 * 64 + (bj * 2 + n) * 16 + fq * 4); }
;                 } else {
; #pragma unroll
;                     for (int bj = 0; bj < 2; ++bj) { h14[bj] = (f32x4){0.f, 0.f, 0.f, 0.f}; h15[bj] = (f32x4){0.f, 0.f, 0.f, 0.f}; } }
; #pragma unroll
;                 for (int m = 0; m < 4; ++m) {
;                     float val[2][4];
; #pragma unroll
;                     for (int bj = 0; bj < 2; ++bj)
; #pragma unroll
;                         for (int jj = 0; jj < 4; ++jj) {
;                             const float cur = acc[ai][bj][m][n][jj];
;                             float o1, o2;
;                             if (m > 0) { const float pv = acc[ai][bj][m > 0 ? m - 1 : 0][n][jj]; o1 = dppf<0x121>(0.f, pv); o2 = dppf<0x122>(0.f, pv); }
;                             else { o1 = h15[bj][jj]; o2 = (fr == 0) ? h14[bj][jj] : h15[bj][jj]; }
;                             const float p1 = dppf<0x111>(o1, cur), p2 = dppf<0x112>(o2, cur);
;                             val[bj][jj] = w2[bj][jj] * cur + w1[bj][jj] * p1 + w0[bj][jj] * p2 + bb[bj][jj];
;                         }
;                     float y[4];
; #pragma unroll
;                     for (int jj = 0; jj < 4; ++jj) { const float g = val[1][jj]; y[jj] = val[0][jj] * g * __builtin_amdgcn_rcpf(1.0f + __builtin_amdgcn_exp2f(-1.4426950408889634f * g)); }
;                     u32x2 w; w.x = cvt_pk_bf16(y[0], y[1]); w.y = cvt_pk_bf16(y[2], y[3]);
	v_pk_fma_f32 v[82:83], v[140:141], v[90:91], v[82:83]
	v_pk_fma_f32 v[80:81], v[130:131], v[118:119], v[80:81]
	v_pk_fma_f32 v[82:83], v[132:133], v[120:121], v[82:83]
	v_pk_fma_f32 v[88:89], v[146:147], v[88:89], v[154:155]
	v_pk_fma_f32 v[90:91], v[148:149], v[90:91], v[156:157]
	v_pk_fma_f32 v[88:89], v[138:139], v[118:119], v[88:89]
	v_pk_fma_f32 v[90:91], v[140:141], v[120:121], v[90:91]
	v_pk_fma_f32 v[88:89], v[130:131], v[170:171], v[88:89]
	v_pk_fma_f32 v[90:91], v[132:133], v[172:173], v[90:91]
	global_load_dwordx4 v[126:129], v112, s[26:27] offset:16
	global_load_dwordx4 v[130:133], v113, s[26:27] offset:16
	global_load_dwordx4 v[134:137], v112, s[58:59] offset:16
	global_load_dwordx4 v[138:141], v113, s[58:59] offset:16
	global_load_dwordx4 v[142:145], v112, s[60:61] offset:16
	global_load_dwordx4 v[146:149], v113, s[60:61] offset:16
	global_load_dwordx4 v[150:153], v112, s[44:45] offset:16
	global_load_dwordx4 v[154:157], v113, s[44:45] offset:16
	v_pk_mul_f32 v[208:209], v[88:89], s[22:23]
	v_pk_mul_f32 v[210:211], v[90:91], s[22:23]
	v_exp_f32_e32 v208, v208
	v_exp_f32_e32 v209, v209
	v_exp_f32_e32 v210, v210
	v_exp_f32_e32 v211, v211
	v_pk_mul_f32 v[92:93], v[92:93], v[88:89]
	v_pk_mul_f32 v[94:95], v[94:95], v[90:91]
	v_pk_add_f32 v[208:209], v[208:209], s[46:47]
	v_pk_add_f32 v[210:211], v[210:211], s[46:47]
	v_rcp_f32_e32 v208, v208
	v_rcp_f32_e32 v209, v209
	v_rcp_f32_e32 v210, v210
	v_rcp_f32_e32 v211, v211
	s_nop 0
	v_pk_mul_f32 v[92:93], v[92:93], v[208:209]
	v_pk_mul_f32 v[94:95], v[94:95], v[210:211]
	v_cvt_pk_bf16_f32 v88, v92, v93
	v_cvt_pk_bf16_f32 v89, v94, v95
	v_pk_mul_f32 v[208:209], v[80:81], s[22:23]
	v_pk_mul_f32 v[210:211], v[82:83], s[22:23]
	v_exp_f32_e32 v208, v208
	v_exp_f32_e32 v209, v209
	v_exp_f32_e32 v210, v210
	v_exp_f32_e32 v211, v211
	v_pk_mul_f32 v[84:85], v[84:85], v[80:81]
	v_pk_mul_f32 v[86:87], v[86:87], v[82:83]
	v_pk_add_f32 v[208:209], v[208:209], s[46:47]
	v_pk_add_f32 v[210:211], v[210:211], s[46:47]
	v_rcp_f32_e32 v208, v208
	v_rcp_f32_e32 v209, v209
	v_rcp_f32_e32 v210, v210
	v_rcp_f32_e32 v211, v211
	s_nop 0
	v_pk_mul_f32 v[84:85], v[84:85], v[208:209]
	v_pk_mul_f32 v[86:87], v[86:87], v[210:211]
	v_cvt_pk_bf16_f32 v80, v84, v85
	v_cvt_pk_bf16_f32 v81, v86, v87
	v_pk_mul_f32 v[208:209], v[68:69], s[22:23]
	v_pk_mul_f32 v[210:211], v[70:71], s[22:23]
	v_exp_f32_e32 v208, v208
	v_exp_f32_e32 v209, v209
	v_exp_f32_e32 v210, v210
	v_exp_f32_e32 v211, v211
	v_pk_mul_f32 v[76:77], v[76:77], v[68:69]
	v_pk_mul_f32 v[78:79], v[78:79], v[70:71]
	v_pk_add_f32 v[208:209], v[208:209], s[46:47]
	v_pk_add_f32 v[210:211], v[210:211], s[46:47]
	v_rcp_f32_e32 v208, v208
	v_rcp_f32_e32 v209, v209
	v_rcp_f32_e32 v210, v210
	v_rcp_f32_e32 v211, v211
	s_nop 0
	v_pk_mul_f32 v[76:77], v[76:77], v[208:209]
	v_pk_mul_f32 v[78:79], v[78:79], v[210:211]
	v_cvt_pk_bf16_f32 v68, v76, v77
	v_cvt_pk_bf16_f32 v69, v78, v79
	v_pk_mul_f32 v[208:209], v[64:65], s[22:23]
	v_pk_mul_f32 v[210:211], v[66:67], s[22:23]
	v_exp_f32_e32 v208, v208
	v_exp_f32_e32 v209, v209
	v_exp_f32_e32 v210, v210
	v_exp_f32_e32 v211, v211
	v_pk_mul_f32 v[72:73], v[72:73], v[64:65]
	v_pk_mul_f32 v[74:75], v[74:75], v[66:67]
	v_pk_add_f32 v[208:209], v[208:209], s[46:47]
	v_pk_add_f32 v[210:211], v[210:211], s[46:47]
	v_rcp_f32_e32 v208, v208
	v_rcp_f32_e32 v209, v209
	v_rcp_f32_e32 v210, v210
	v_rcp_f32_e32 v211, v211
	s_nop 0
	v_pk_mul_f32 v[72:73], v[72:73], v[208:209]
	v_pk_mul_f32 v[74:75], v[74:75], v[210:211]
	v_cvt_pk_bf16_f32 v64, v72, v73
	v_cvt_pk_bf16_f32 v65, v74, v75
	v_mov_b32_e32 v166, 0
	v_mov_b32_e32 v174, 0
	v_mov_b32_e32 v167, 0
	v_mov_b32_e32 v175, 0
	v_mov_b32_e32 v168, 0
	v_mov_b32_e32 v176, 0
	v_mov_b32_e32 v169, 0
	v_mov_b32_e32 v177, 0
	v_mov_b32_e32 v170, 0
	v_mov_b32_e32 v118, 0
	v_mov_b32_e32 v171, 0
	v_mov_b32_e32 v119, 0
	v_mov_b32_e32 v172, 0
	v_mov_b32_e32 v120, 0
	v_mov_b32_e32 v173, 0
	v_mov_b32_e32 v121, 0
	s_and_b64 vcc, exec, s[36:37]
	s_cbranch_vccz .Lffn_h10
	ds_read_b128 v[166:169], v214 offset:64
	ds_read_b128 v[174:177], v214 offset:320
	ds_read_b128 v[170:173], v214 offset:192
	ds_read_b128 v[118:121], v214 offset:448
.Lffn_h10:
	s_waitcnt vmcnt(0) lgkmcnt(0)
	v_mov_b32_dpp v174, v40 row_shr:1 row_mask:0xf bank_mask:0xf
	v_mov_b32_dpp v175, v41 row_shr:1 row_mask:0xf bank_mask:0xf
	v_mov_b32_dpp v176, v42 row_shr:1 row_mask:0xf bank_mask:0xf
	v_mov_b32_dpp v177, v43 row_shr:1 row_mask:0xf bank_mask:0xf
	v_mov_b32_dpp v166, v44 row_shr:1 row_mask:0xf bank_mask:0xf
	v_mov_b32_dpp v167, v45 row_shr:1 row_mask:0xf bank_mask:0xf
	v_mov_b32_dpp v168, v46 row_shr:1 row_mask:0xf bank_mask:0xf
	v_mov_b32_dpp v169, v47 row_shr:1 row_mask:0xf bank_mask:0xf
	v_pk_fma_f32 v[40:41], v[142:143], v[40:41], v[150:151]
	v_pk_fma_f32 v[42:43], v[144:145], v[42:43], v[152:153]
	v_pk_fma_f32 v[40:41], v[134:135], v[44:45], v[40:41]
	v_pk_fma_f32 v[42:43], v[136:137], v[46:47], v[42:43]
	v_pk_fma_f32 v[40:41], v[126:127], v[52:53], v[40:41]
	v_pk_fma_f32 v[42:43], v[128:129], v[54:55], v[42:43]
	v_pk_fma_f32 v[44:45], v[142:143], v[44:45], v[150:151]
	v_pk_fma_f32 v[46:47], v[144:145], v[46:47], v[152:153]
	v_pk_fma_f32 v[44:45], v[134:135], v[52:53], v[44:45]
	v_pk_fma_f32 v[46:47], v[136:137], v[54:55], v[46:47]
	v_pk_fma_f32 v[44:45], v[126:127], v[60:61], v[44:45]
	v_pk_fma_f32 v[46:47], v[128:129], v[62:63], v[46:47]
	v_pk_fma_f32 v[52:53], v[142:143], v[52:53], v[150:151]
	v_pk_fma_f32 v[54:55], v[144:145], v[54:55], v[152:153]
	v_pk_fma_f32 v[52:53], v[134:135], v[60:61], v[52:53]
	v_pk_fma_f32 v[54:55], v[136:137], v[62:63], v[54:55]
	v_pk_fma_f32 v[52:53], v[126:127], v[174:175], v[52:53]
; __device__ __forceinline__ unsigned cvt_pk_bf16(float lo, float hi) { unsigned r; asm volatile("v_cvt_pk_bf16_f32 %0, %1, %2" : "=v"(r) : "v"(lo), "v"(hi)); return r; }
;     __device__ __forceinline__ void operator()(const f32x4 (&acc)[2][2][4][2], const Unit& u, int wr, int wc, int fr, int fq) const {
;     ...
;                 for (int m = 0; m < 4; ++m) {
;                     float val[2][4];
; #pragma unroll
;                     for (int bj = 0; bj < 2; ++bj)
; #pragma unroll
;                         for (int jj = 0; jj < 4; ++jj) {
;                             const float cur = acc[ai][bj][m][n][jj];
;                             float o1, o2;
;                             if (m > 0) { const float pv = acc[ai][bj][m > 0 ? m - 1 : 0][n][jj]; o1 = dppf<0x121>(0.f, pv); o2 = dppf<0x122>(0.f, pv); }
;                             else { o1 = h15[bj][jj]; o2 = (fr == 0) ? h14[bj][jj] : h15[bj][jj]; }
;                             const float p1 = dppf<0x111>(o1, cur), p2 = dppf<0x112>(o2, cur);
;                             val[bj][jj] = w2[bj][jj] * cur + w1[bj][jj] * p1 + w0[bj][jj] * p2 + bb[bj][jj];
;                         }
;                     float y[4];
; #pragma unroll
;                     for (int jj = 0; jj < 4; ++jj) { const float g = val[1][jj]; y[jj] = val[0][jj] * g * __builtin_amdgcn_rcpf(1.0f + __builtin_amdgcn_exp2f(-1.4426950408889634f * g)); }
;                     u32x2 w; w.x = cvt_pk_bf16(y[0], y[1]); w.y = cvt_pk_bf16(y[2], y[3]);
;                     if (n == 0) keep[ai][m] = w;
;                     else { const int row = u.pm * BM + ai * HALF + wr * 64 + m * 16 + fr;
;                         u32x4 w4; w4.x = keep[ai][m].x; w4.y = keep[ai][m].y; w4.z = w.x; w4.w = w.y;
;                         *(u32x4*)(act + (size_t)row * dff + ch0 - 4) = w4; }
	v_pk_fma_f32 v[54:55], v[128:129], v[176:177], v[54:55]
	v_pk_fma_f32 v[60:61], v[142:143], v[60:61], v[150:151]
	v_pk_fma_f32 v[62:63], v[144:145], v[62:63], v[152:153]
	v_pk_fma_f32 v[60:61], v[134:135], v[174:175], v[60:61]
	v_pk_fma_f32 v[62:63], v[136:137], v[176:177], v[62:63]
	v_pk_fma_f32 v[60:61], v[126:127], v[166:167], v[60:61]
	v_pk_fma_f32 v[62:63], v[128:129], v[168:169], v[62:63]
	v_mov_b32_dpp v118, v32 row_shr:1 row_mask:0xf bank_mask:0xf
	v_mov_b32_dpp v119, v33 row_shr:1 row_mask:0xf bank_mask:0xf
	v_mov_b32_dpp v120, v34 row_shr:1 row_mask:0xf bank_mask:0xf
	v_mov_b32_dpp v121, v35 row_shr:1 row_mask:0xf bank_mask:0xf
	v_mov_b32_dpp v170, v36 row_shr:1 row_mask:0xf bank_mask:0xf
	v_mov_b32_dpp v171, v37 row_shr:1 row_mask:0xf bank_mask:0xf
	v_mov_b32_dpp v172, v38 row_shr:1 row_mask:0xf bank_mask:0xf
	v_mov_b32_dpp v173, v39 row_shr:1 row_mask:0xf bank_mask:0xf
	v_pk_fma_f32 v[32:33], v[146:147], v[32:33], v[154:155]
	v_pk_fma_f32 v[34:35], v[148:149], v[34:35], v[156:157]
	v_pk_fma_f32 v[32:33], v[138:139], v[36:37], v[32:33]
	v_pk_fma_f32 v[34:35], v[140:141], v[38:39], v[34:35]
	v_pk_fma_f32 v[32:33], v[130:131], v[48:49], v[32:33]
	v_pk_fma_f32 v[34:35], v[132:133], v[50:51], v[34:35]
	v_pk_fma_f32 v[36:37], v[146:147], v[36:37], v[154:155]
	v_pk_fma_f32 v[38:39], v[148:149], v[38:39], v[156:157]
	v_pk_fma_f32 v[36:37], v[138:139], v[48:49], v[36:37]
	v_pk_fma_f32 v[38:39], v[140:141], v[50:51], v[38:39]
	v_pk_fma_f32 v[36:37], v[130:131], v[56:57], v[36:37]
	v_pk_fma_f32 v[38:39], v[132:133], v[58:59], v[38:39]
	v_pk_fma_f32 v[48:49], v[146:147], v[48:49], v[154:155]
	v_pk_fma_f32 v[50:51], v[148:149], v[50:51], v[156:157]
	v_pk_fma_f32 v[48:49], v[138:139], v[56:57], v[48:49]
	v_pk_fma_f32 v[50:51], v[140:141], v[58:59], v[50:51]
	v_pk_fma_f32 v[48:49], v[130:131], v[118:119], v[48:49]
	v_pk_fma_f32 v[50:51], v[132:133], v[120:121], v[50:51]
	v_pk_fma_f32 v[56:57], v[146:147], v[56:57], v[154:155]
	v_pk_fma_f32 v[58:59], v[148:149], v[58:59], v[156:157]
	v_pk_fma_f32 v[56:57], v[138:139], v[118:119], v[56:57]
	v_pk_fma_f32 v[58:59], v[140:141], v[120:121], v[58:59]
	v_pk_fma_f32 v[56:57], v[130:131], v[170:171], v[56:57]
	v_pk_fma_f32 v[58:59], v[132:133], v[172:173], v[58:59]
	v_pk_mul_f32 v[208:209], v[56:57], s[22:23]
	v_pk_mul_f32 v[210:211], v[58:59], s[22:23]
	v_exp_f32_e32 v208, v208
	v_exp_f32_e32 v209, v209
	v_exp_f32_e32 v210, v210
	v_exp_f32_e32 v211, v211
	v_pk_mul_f32 v[60:61], v[60:61], v[56:57]
	v_pk_mul_f32 v[62:63], v[62:63], v[58:59]
	v_pk_add_f32 v[208:209], v[208:209], s[46:47]
	v_pk_add_f32 v[210:211], v[210:211], s[46:47]
	v_rcp_f32_e32 v208, v208
	v_rcp_f32_e32 v209, v209
	v_rcp_f32_e32 v210, v210
	v_rcp_f32_e32 v211, v211
	s_nop 0
	v_pk_mul_f32 v[60:61], v[60:61], v[208:209]
	v_pk_mul_f32 v[62:63], v[62:63], v[210:211]
	v_cvt_pk_bf16_f32 v160, v60, v61
	v_cvt_pk_bf16_f32 v161, v62, v63
	global_store_dwordx4 v188, v[158:161], s[30:31]
	s_add_u32 s30, s30, 0x2c00
	s_addc_u32 s31, s31, 0
	v_pk_mul_f32 v[208:209], v[48:49], s[22:23]
	v_pk_mul_f32 v[210:211], v[50:51], s[22:23]
	v_exp_f32_e32 v208, v208
	v_exp_f32_e32 v209, v209
	v_exp_f32_e32 v210, v210
	v_exp_f32_e32 v211, v211
	v_pk_mul_f32 v[52:53], v[52:53], v[48:49]
	v_pk_mul_f32 v[54:55], v[54:55], v[50:51]
	v_pk_add_f32 v[208:209], v[208:209], s[46:47]
	v_pk_add_f32 v[210:211], v[210:211], s[46:47]
	v_rcp_f32_e32 v208, v208
	v_rcp_f32_e32 v209, v209
	v_rcp_f32_e32 v210, v210
	v_rcp_f32_e32 v211, v211
	s_nop 0
	v_pk_mul_f32 v[52:53], v[52:53], v[208:209]
	v_pk_mul_f32 v[54:55], v[54:55], v[210:211]
	v_cvt_pk_bf16_f32 v116, v52, v53
	v_cvt_pk_bf16_f32 v117, v54, v55
	global_store_dwordx4 v188, v[114:117], s[30:31]
	s_add_u32 s30, s30, 0x2c00
	s_addc_u32 s31, s31, 0
	v_pk_mul_f32 v[208:209], v[36:37], s[22:23]
	v_pk_mul_f32 v[210:211], v[38:39], s[22:23]
	v_exp_f32_e32 v208, v208
	v_exp_f32_e32 v209, v209
	v_exp_f32_e32 v210, v210
	v_exp_f32_e32 v211, v211
	v_pk_mul_f32 v[44:45], v[44:45], v[36:37]
	v_pk_mul_f32 v[46:47], v[46:47], v[38:39]
	v_pk_add_f32 v[208:209], v[208:209], s[46:47]
	v_pk_add_f32 v[210:211], v[210:211], s[46:47]
	v_rcp_f32_e32 v208, v208
	v_rcp_f32_e32 v209, v209
	v_rcp_f32_e32 v210, v210
	v_rcp_f32_e32 v211, v211
	s_nop 0
	v_pk_mul_f32 v[44:45], v[44:45], v[208:209]
	v_pk_mul_f32 v[46:47], v[46:47], v[210:211]
	v_cvt_pk_bf16_f32 v102, v44, v45
	v_cvt_pk_bf16_f32 v103, v46, v47
	global_store_dwordx4 v188, v[100:103], s[30:31]
	s_add_u32 s30, s30, 0x2c00
	s_addc_u32 s31, s31, 0
	v_pk_mul_f32 v[208:209], v[32:33], s[22:23]
	v_pk_mul_f32 v[210:211], v[34:35], s[22:23]
	v_exp_f32_e32 v208, v208
	v_exp_f32_e32 v209, v209
	v_exp_f32_e32 v210, v210
	v_exp_f32_e32 v211, v211
	v_pk_mul_f32 v[40:41], v[40:41], v[32:33]
	v_pk_mul_f32 v[42:43], v[42:43], v[34:35]
	v_pk_add_f32 v[208:209], v[208:209], s[46:47]
	v_pk_add_f32 v[210:211], v[210:211], s[46:47]
	v_rcp_f32_e32 v208, v208
	v_rcp_f32_e32 v209, v209
	v_rcp_f32_e32 v210, v210
	v_rcp_f32_e32 v211, v211
	s_nop 0
	v_pk_mul_f32 v[40:41], v[40:41], v[208:209]
	v_pk_mul_f32 v[42:43], v[42:43], v[210:211]
	v_cvt_pk_bf16_f32 v98, v40, v41
	v_cvt_pk_bf16_f32 v99, v42, v43
	global_store_dwordx4 v188, v[96:99], s[30:31]
	s_add_u32 s30, s30, 0x157c00
	s_addc_u32 s31, s31, 0
	ds_read_b128 v[166:169], v206 offset:64
	ds_read_b128 v[174:177], v206 offset:320
	ds_read_b128 v[170:173], v206 offset:192
	ds_read_b128 v[118:121], v206 offset:448
	s_waitcnt lgkmcnt(0)
; #define PG8_BAR __builtin_amdgcn_s_barrier()
;     __device__ __forceinline__ void operator()(const f32x4 (&acc)[2][2][4][2], const Unit& u, int wr, int wc, int fr, int fq) const {
;     ...
;                 for (int m = 0; m < 4; ++m) {
;                     float val[2][4];
; #pragma unroll
;                     for (int bj = 0; bj < 2; ++bj)
; #pragma unroll
;                         for (int jj = 0; jj < 4; ++jj) {
;                             const float cur = acc[ai][bj][m][n][jj];
;                             float o1, o2;
;                             if (m > 0) { const float pv = acc[ai][bj][m > 0 ? m - 1 : 0][n][jj]; o1 = dppf<0x121>(0.f, pv); o2 = dppf<0x122>(0.f, pv); }
;                             else { o1 = h15[bj][jj]; o2 = (fr == 0) ? h14[bj][jj] : h15[bj][jj]; }
;                             const float p1 = dppf<0x111>(o1, cur), p2 = dppf<0x112>(o2, cur);
;                             val[bj][jj] = w2[bj][jj] * cur + w1[bj][jj] * p1 + w0[bj][jj] * p2 + bb[bj][jj];
;                         }
;                     float y[4];
; #pragma unroll
;                     for (int jj = 0; jj < 4; ++jj) { const float g = val[1][jj]; y[jj] = val[0][jj] * g * __builtin_amdgcn_rcpf(1.0f + __builtin_amdgcn_exp2f(-1.4426950408889634f * g)); }
;                     u32x2 w; w.x = cvt_pk_bf16(y[0], y[1]); w.y = cvt_pk_bf16(y[2], y[3]);
;                     if (n == 0) keep[ai][m] = w;
;                     else { const int row = u.pm * BM + ai * HALF + wr * 64 + m * 16 + fr;
;                         u32x4 w4; w4.x = keep[ai][m].x; w4.y = keep[ai][m].y; w4.z = w.x; w4.w = w.y;
;                         *(u32x4*)(act + (size_t)row * dff + ch0 - 4) = w4; }
; template <class Epi, class Sched, bool ALIGN_EPI = false, bool SP2 = false>
; __device__ __forceinline__ void gemm_phase(PG8_LAS unsigned char* lds, const Gemm g, const Sched& S, const Epi& E) {
;     ...
;         if (!has_next) break;
; #pragma unroll
;         for (int a = 0; a < 2; ++a)
; #pragma unroll
;             for (int b = 0; b < 2; ++b)
; #pragma unroll
;                 for (int m = 0; m < 4; ++m)
; #pragma unroll
;                     for (int n = 0; n < 2; ++n) acc[a][b][m][n] = (f32x4){0.f, 0.f, 0.f, 0.f};
;         cur = nxt; cA = nA; cB = nB; ++ui;
;         if constexpr (ALIGN_EPI) { if (wr == 1) PG8_BAR; }
	v_mov_b32_dpp v174, v8 row_shr:1 row_mask:0xf bank_mask:0xf
	v_mov_b32_dpp v175, v9 row_shr:1 row_mask:0xf bank_mask:0xf
	v_mov_b32_dpp v176, v10 row_shr:1 row_mask:0xf bank_mask:0xf
	v_mov_b32_dpp v177, v11 row_shr:1 row_mask:0xf bank_mask:0xf
	v_mov_b32_dpp v166, v12 row_shr:1 row_mask:0xf bank_mask:0xf
	v_mov_b32_dpp v167, v13 row_shr:1 row_mask:0xf bank_mask:0xf
	v_mov_b32_dpp v168, v14 row_shr:1 row_mask:0xf bank_mask:0xf
	v_mov_b32_dpp v169, v15 row_shr:1 row_mask:0xf bank_mask:0xf
	v_pk_fma_f32 v[8:9], v[142:143], v[8:9], v[150:151]
	v_pk_fma_f32 v[10:11], v[144:145], v[10:11], v[152:153]
	v_pk_fma_f32 v[8:9], v[134:135], v[12:13], v[8:9]
	v_pk_fma_f32 v[10:11], v[136:137], v[14:15], v[10:11]
	v_pk_fma_f32 v[8:9], v[126:127], v[20:21], v[8:9]
	v_pk_fma_f32 v[10:11], v[128:129], v[22:23], v[10:11]
	v_pk_fma_f32 v[12:13], v[142:143], v[12:13], v[150:151]
	v_pk_fma_f32 v[14:15], v[144:145], v[14:15], v[152:153]
	v_pk_fma_f32 v[12:13], v[134:135], v[20:21], v[12:13]
	v_pk_fma_f32 v[14:15], v[136:137], v[22:23], v[14:15]
	v_pk_fma_f32 v[12:13], v[126:127], v[28:29], v[12:13]
	v_pk_fma_f32 v[14:15], v[128:129], v[30:31], v[14:15]
	v_pk_fma_f32 v[20:21], v[142:143], v[20:21], v[150:151]
	v_pk_fma_f32 v[22:23], v[144:145], v[22:23], v[152:153]
	v_pk_fma_f32 v[20:21], v[134:135], v[28:29], v[20:21]
	v_pk_fma_f32 v[22:23], v[136:137], v[30:31], v[22:23]
	v_pk_fma_f32 v[20:21], v[126:127], v[174:175], v[20:21]
	v_pk_fma_f32 v[22:23], v[128:129], v[176:177], v[22:23]
	v_pk_fma_f32 v[28:29], v[142:143], v[28:29], v[150:151]
	v_pk_fma_f32 v[30:31], v[144:145], v[30:31], v[152:153]
	v_pk_fma_f32 v[28:29], v[134:135], v[174:175], v[28:29]
	v_pk_fma_f32 v[30:31], v[136:137], v[176:177], v[30:31]
	v_pk_fma_f32 v[28:29], v[126:127], v[166:167], v[28:29]
	v_pk_fma_f32 v[30:31], v[128:129], v[168:169], v[30:31]
	v_mov_b32_dpp v118, v0 row_shr:1 row_mask:0xf bank_mask:0xf
	v_mov_b32_dpp v119, v1 row_shr:1 row_mask:0xf bank_mask:0xf
	v_mov_b32_dpp v120, v2 row_shr:1 row_mask:0xf bank_mask:0xf
	v_mov_b32_dpp v121, v3 row_shr:1 row_mask:0xf bank_mask:0xf
	v_mov_b32_dpp v170, v4 row_shr:1 row_mask:0xf bank_mask:0xf
	v_mov_b32_dpp v171, v5 row_shr:1 row_mask:0xf bank_mask:0xf
	v_mov_b32_dpp v172, v6 row_shr:1 row_mask:0xf bank_mask:0xf
	v_mov_b32_dpp v173, v7 row_shr:1 row_mask:0xf bank_mask:0xf
	v_pk_fma_f32 v[0:1], v[146:147], v[0:1], v[154:155]
	v_pk_fma_f32 v[2:3], v[148:149], v[2:3], v[156:157]
	v_pk_fma_f32 v[0:1], v[138:139], v[4:5], v[0:1]
	v_pk_fma_f32 v[2:3], v[140:141], v[6:7], v[2:3]
	v_pk_fma_f32 v[0:1], v[130:131], v[16:17], v[0:1]
	v_pk_fma_f32 v[2:3], v[132:133], v[18:19], v[2:3]
	v_pk_fma_f32 v[4:5], v[146:147], v[4:5], v[154:155]
	v_pk_fma_f32 v[6:7], v[148:149], v[6:7], v[156:157]
	v_pk_fma_f32 v[4:5], v[138:139], v[16:17], v[4:5]
	v_pk_fma_f32 v[6:7], v[140:141], v[18:19], v[6:7]
	v_pk_fma_f32 v[4:5], v[130:131], v[24:25], v[4:5]
	v_pk_fma_f32 v[6:7], v[132:133], v[26:27], v[6:7]
	v_pk_fma_f32 v[16:17], v[146:147], v[16:17], v[154:155]
	v_pk_fma_f32 v[18:19], v[148:149], v[18:19], v[156:157]
	v_pk_fma_f32 v[16:17], v[138:139], v[24:25], v[16:17]
	v_pk_fma_f32 v[18:19], v[140:141], v[26:27], v[18:19]
	v_pk_fma_f32 v[16:17], v[130:131], v[118:119], v[16:17]
	v_pk_fma_f32 v[18:19], v[132:133], v[120:121], v[18:19]
	v_pk_fma_f32 v[24:25], v[146:147], v[24:25], v[154:155]
	v_pk_fma_f32 v[26:27], v[148:149], v[26:27], v[156:157]
	v_pk_fma_f32 v[24:25], v[138:139], v[118:119], v[24:25]
	v_pk_fma_f32 v[26:27], v[140:141], v[120:121], v[26:27]
	v_pk_fma_f32 v[24:25], v[130:131], v[170:171], v[24:25]
	v_pk_fma_f32 v[26:27], v[132:133], v[172:173], v[26:27]
	v_pk_mul_f32 v[208:209], v[24:25], s[22:23]
	v_pk_mul_f32 v[210:211], v[26:27], s[22:23]
	v_exp_f32_e32 v208, v208
	v_exp_f32_e32 v209, v209
	v_exp_f32_e32 v210, v210
	v_exp_f32_e32 v211, v211
	v_pk_mul_f32 v[28:29], v[28:29], v[24:25]
	v_pk_mul_f32 v[30:31], v[30:31], v[26:27]
	v_pk_add_f32 v[208:209], v[208:209], s[46:47]
	v_pk_add_f32 v[210:211], v[210:211], s[46:47]
	v_rcp_f32_e32 v208, v208
	v_rcp_f32_e32 v209, v209
	v_rcp_f32_e32 v210, v210
	v_rcp_f32_e32 v211, v211
	s_nop 0
	v_pk_mul_f32 v[28:29], v[28:29], v[208:209]
	v_pk_mul_f32 v[30:31], v[30:31], v[210:211]
	v_cvt_pk_bf16_f32 v90, v28, v29
	v_cvt_pk_bf16_f32 v91, v30, v31
	global_store_dwordx4 v188, v[88:91], s[30:31]
	s_add_u32 s30, s30, 0x2c00
	s_addc_u32 s31, s31, 0
	v_pk_mul_f32 v[208:209], v[16:17], s[22:23]
	v_pk_mul_f32 v[210:211], v[18:19], s[22:23]
	v_exp_f32_e32 v208, v208
	v_exp_f32_e32 v209, v209
	v_exp_f32_e32 v210, v210
	v_exp_f32_e32 v211, v211
	v_pk_mul_f32 v[20:21], v[20:21], v[16:17]
	v_pk_mul_f32 v[22:23], v[22:23], v[18:19]
	v_pk_add_f32 v[208:209], v[208:209], s[46:47]
	v_pk_add_f32 v[210:211], v[210:211], s[46:47]
	v_rcp_f32_e32 v208, v208
	v_rcp_f32_e32 v209, v209
	v_rcp_f32_e32 v210, v210
	v_rcp_f32_e32 v211, v211
	s_nop 0
	v_pk_mul_f32 v[20:21], v[20:21], v[208:209]
	v_pk_mul_f32 v[22:23], v[22:23], v[210:211]
	v_cvt_pk_bf16_f32 v82, v20, v21
	v_cvt_pk_bf16_f32 v83, v22, v23
	global_store_dwordx4 v188, v[80:83], s[30:31]
	s_add_u32 s30, s30, 0x2c00
	s_addc_u32 s31, s31, 0
	v_pk_mul_f32 v[208:209], v[4:5], s[22:23]
	v_pk_mul_f32 v[210:211], v[6:7], s[22:23]
	v_exp_f32_e32 v208, v208
	v_exp_f32_e32 v209, v209
	v_exp_f32_e32 v210, v210
	v_exp_f32_e32 v211, v211
	v_pk_mul_f32 v[12:13], v[12:13], v[4:5]
	v_pk_mul_f32 v[14:15], v[14:15], v[6:7]
	v_pk_add_f32 v[208:209], v[208:209], s[46:47]
	v_pk_add_f32 v[210:211], v[210:211], s[46:47]
	v_rcp_f32_e32 v208, v208
	v_rcp_f32_e32 v209, v209
	v_rcp_f32_e32 v210, v210
	v_rcp_f32_e32 v211, v211
	s_nop 0
	v_pk_mul_f32 v[12:13], v[12:13], v[208:209]
	v_pk_mul_f32 v[14:15], v[14:15], v[210:211]
	v_cvt_pk_bf16_f32 v70, v12, v13
	v_cvt_pk_bf16_f32 v71, v14, v15
	global_store_dwordx4 v188, v[68:71], s[30:31]
	s_add_u32 s30, s30, 0x2c00
	s_addc_u32 s31, s31, 0
	v_pk_mul_f32 v[208:209], v[0:1], s[22:23]
	v_pk_mul_f32 v[210:211], v[2:3], s[22:23]
	v_exp_f32_e32 v208, v208
	v_exp_f32_e32 v209, v209
	v_exp_f32_e32 v210, v210
	v_exp_f32_e32 v211, v211
	v_pk_mul_f32 v[8:9], v[8:9], v[0:1]
	v_pk_mul_f32 v[10:11], v[10:11], v[2:3]
	v_pk_add_f32 v[208:209], v[208:209], s[46:47]
	v_pk_add_f32 v[210:211], v[210:211], s[46:47]
	v_rcp_f32_e32 v208, v208
	v_rcp_f32_e32 v209, v209
	v_rcp_f32_e32 v210, v210
	v_rcp_f32_e32 v211, v211
	s_nop 0
	v_pk_mul_f32 v[8:9], v[8:9], v[208:209]
	v_pk_mul_f32 v[10:11], v[10:11], v[210:211]
	v_cvt_pk_bf16_f32 v66, v8, v9
	v_cvt_pk_bf16_f32 v67, v10, v11
	global_store_dwordx4 v188, v[64:67], s[30:31]
	s_not_b64 s[10:11], s[36:37]
	s_andn2_b64 vcc, exec, s[8:9]
	s_mov_b64 s[8:9], -1
	s_cbranch_vccnz .LBB0_400
	s_and_b64 vcc, exec, s[10:11]
	s_cbranch_vccnz .LBB0_399
	s_barrier
	s_branch .LBB0_399

; template <class Epi, class Sched, bool ALIGN_EPI = false, bool SP2 = false>
; __device__ __forceinline__ void gemm_phase(PG8_LAS unsigned char* lds, const Gemm g, const Sched& S, const Epi& E) {
;     ...
; #pragma unroll
;         for (int a = 0; a < 2; ++a)
; #pragma unroll
;             for (int b = 0; b < 2; ++b)
; #pragma unroll
;                 for (int m = 0; m < 4; ++m)
; #pragma unroll
;                     for (int n = 0; n < 2; ++n) acc[a][b][m][n] = (f32x4){0.f, 0.f, 0.f, 0.f};
;         cur = nxt; cA = nA; cB = nB; ++ui;
.LBB0_551:
	s_add_u32 s65, s34, 0x100
	s_addc_u32 s66, s35, 0
	s_mov_b32 s67, -2
	v_mov_b64_e32 v[0:1], 0
	v_mov_b64_e32 v[2:3], 0
	v_mov_b64_e32 v[4:5], 0
	v_mov_b64_e32 v[6:7], 0
	v_mov_b64_e32 v[8:9], 0
	v_mov_b64_e32 v[10:11], 0
	v_mov_b64_e32 v[12:13], 0
	v_mov_b64_e32 v[14:15], 0
	v_mov_b64_e32 v[16:17], 0
	v_mov_b64_e32 v[18:19], 0
	v_mov_b64_e32 v[20:21], 0
	v_mov_b64_e32 v[22:23], 0
	v_mov_b64_e32 v[24:25], 0
	v_mov_b64_e32 v[26:27], 0
	v_mov_b64_e32 v[28:29], 0
	v_mov_b64_e32 v[30:31], 0
	v_mov_b64_e32 v[32:33], 0
	v_mov_b64_e32 v[34:35], 0
	v_mov_b64_e32 v[36:37], 0
	v_mov_b64_e32 v[38:39], 0
	v_mov_b64_e32 v[40:41], 0
	v_mov_b64_e32 v[42:43], 0
	v_mov_b64_e32 v[44:45], 0
	v_mov_b64_e32 v[46:47], 0
	v_mov_b64_e32 v[48:49], 0
	v_mov_b64_e32 v[50:51], 0
	v_mov_b64_e32 v[52:53], 0
	v_mov_b64_e32 v[54:55], 0
	v_mov_b64_e32 v[56:57], 0
	v_mov_b64_e32 v[58:59], 0
	v_mov_b64_e32 v[60:61], 0
	v_mov_b64_e32 v[62:63], 0
	v_mov_b64_e32 v[64:65], 0
	v_mov_b64_e32 v[66:67], 0
	v_mov_b64_e32 v[68:69], 0
	v_mov_b64_e32 v[70:71], 0
	v_mov_b64_e32 v[72:73], 0
	v_mov_b64_e32 v[74:75], 0
	v_mov_b64_e32 v[76:77], 0
	v_mov_b64_e32 v[78:79], 0
	v_mov_b64_e32 v[80:81], 0
	v_mov_b64_e32 v[82:83], 0
	v_mov_b64_e32 v[84:85], 0
	v_mov_b64_e32 v[86:87], 0
	v_mov_b64_e32 v[88:89], 0
	v_mov_b64_e32 v[90:91], 0
	v_mov_b64_e32 v[92:93], 0
	v_mov_b64_e32 v[94:95], 0
	v_mov_b64_e32 v[96:97], 0
	v_mov_b64_e32 v[98:99], 0
	v_mov_b64_e32 v[100:101], 0
	v_mov_b64_e32 v[102:103], 0
	v_mov_b64_e32 v[104:105], 0
	v_mov_b64_e32 v[106:107], 0
	v_mov_b64_e32 v[108:109], 0
	v_mov_b64_e32 v[110:111], 0
	v_mov_b64_e32 v[112:113], 0
	v_mov_b64_e32 v[114:115], 0
	v_mov_b64_e32 v[116:117], 0
	v_mov_b64_e32 v[118:119], 0
	v_mov_b64_e32 v[120:121], 0
	v_mov_b64_e32 v[122:123], 0
	v_mov_b64_e32 v[124:125], 0
	v_mov_b64_e32 v[126:127], 0
